# T4 fast path with nt on its 64 streaming K/V cache loads
# baseline (speedup 1.0000x reference)
.LBB0_253:
	s_waitcnt vmcnt(3)
	v_ashrrev_i32_e32 v0, 6, v206
	s_waitcnt vmcnt(2)
	v_and_b32_e32 v4, 63, v206
	v_cmp_lt_i32_e32 vcc, 5, v0
	s_and_saveexec_b64 s[2:3], vcc
	s_xor_b64 s[2:3], exec, s[2:3]
	s_cbranch_execz .LBB0_301
	v_lshl_add_u32 v0, s90, 7, v206
	v_add_u32_e32 v6, 0xfffffe80, v0
	s_lshl_b32 s4, s74, 7
	v_cmp_gt_i32_e32 vcc, s31, v6
	v_and_b32_e32 v2, 0x7f, v206
	v_ashrrev_i32_e32 v7, 31, v6
	s_and_saveexec_b64 s[6:7], vcc
	s_cbranch_execz .LBB0_271
	s_load_dwordx4 s[52:55], s[0:1], 0x10
	s_add_u32 s8, s72, 0xe9c8000
	s_addc_u32 s9, s73, 0
	s_waitcnt lgkmcnt(0)
	s_add_u32 s10, s72, 0xec48000
	s_addc_u32 s11, s73, 0
	s_lshl_b32 s12, s74, 10
	s_ashr_i32 s13, s12, 31
	v_lshl_add_u64 v[0:1], v[6:7], 2, s[52:53]
	s_lshl_b64 s[14:15], s[12:13], 2
	s_lshl_b32 s5, s74, 8
	s_lshl_b32 s13, s74, 9
	s_mov_b64 s[26:27], 0
	v_mov_b32_e32 v3, v6
	v_bfe_u32 v44, v6, 3, 3
	v_lshrrev_b32_e32 v45, 7, v6
	v_and_b32_e32 v45, 0x78, v45
	v_or_b32_e32 v44, v44, v45
	v_lshrrev_b32_e32 v45, 3, v6
	v_and_b32_e32 v45, 0x78, v45
	v_and_or_b32 v45, v6, 7, v45
	s_cmpk_lg_i32 s74, 0x100
	s_cbranch_scc1 .LBB0_257
	s_cmp_lg_u32 s31, 0x100000
	s_cbranch_scc1 .LBB0_257
	v_and_b32_e32 v3, 0x3fff, v6
	v_lshrrev_b32_e32 v5, 14, v6
	v_lshlrev_b32_e32 v0, 2, v6
	v_lshl_or_b32 v1, v44, 7, v45
	v_lshlrev_b32_e32 v1, 2, v1
	v_lshl_add_u32 v1, v5, 16, v1
	v_mul_u32_u24_e32 v5, 0xa000, v5
	v_lshl_add_u32 v3, v3, 1, v5
	v_mul_u32_u24_e32 v21, 0x140, v45
	v_lshl_add_u32 v21, v44, 1, v21
	v_add_u32_e32 v5, v5, v21
	s_mov_b64 s[38:39], s[52:53]
	s_mov_b64 s[40:41], s[54:55]
	s_mov_b64 s[44:45], s[8:9]
	s_mov_b64 s[46:47], s[10:11]
	global_load_dword v8, v0, s[38:39] nt
	global_load_dword v9, v1, s[40:41] nt
	s_add_u32 s38, s38, 0x20000
	s_addc_u32 s39, s39, 0
	s_add_u32 s40, s40, 0x20000
	s_addc_u32 s41, s41, 0
	global_load_dword v10, v0, s[38:39] nt
	global_load_dword v11, v1, s[40:41] nt
	s_add_u32 s38, s38, 0x20000
	s_addc_u32 s39, s39, 0
	s_add_u32 s40, s40, 0x20000
	s_addc_u32 s41, s41, 0
	global_load_dword v12, v0, s[38:39] nt
	global_load_dword v13, v1, s[40:41] nt
	s_add_u32 s38, s38, 0x20000
	s_addc_u32 s39, s39, 0
	s_add_u32 s40, s40, 0x20000
	s_addc_u32 s41, s41, 0
	global_load_dword v14, v0, s[38:39] nt
	global_load_dword v15, v1, s[40:41] nt
	s_add_u32 s38, s38, 0x20000
	s_addc_u32 s39, s39, 0
	s_add_u32 s40, s40, 0x20000
	s_addc_u32 s41, s41, 0
	global_load_dword v16, v0, s[38:39] nt
	global_load_dword v17, v1, s[40:41] nt
	s_add_u32 s38, s38, 0x20000
	s_addc_u32 s39, s39, 0
	s_add_u32 s40, s40, 0x20000
	s_addc_u32 s41, s41, 0
	global_load_dword v18, v0, s[38:39] nt
	global_load_dword v19, v1, s[40:41] nt
	s_add_u32 s38, s38, 0x20000
	s_addc_u32 s39, s39, 0
	s_add_u32 s40, s40, 0x20000
	s_addc_u32 s41, s41, 0
	global_load_dword v21, v0, s[38:39] nt
	global_load_dword v22, v1, s[40:41] nt
	s_add_u32 s38, s38, 0x20000
	s_addc_u32 s39, s39, 0
	s_add_u32 s40, s40, 0x20000
	s_addc_u32 s41, s41, 0
	global_load_dword v23, v0, s[38:39] nt
	global_load_dword v24, v1, s[40:41] nt
	s_add_u32 s38, s38, 0x20000
	s_addc_u32 s39, s39, 0
	s_add_u32 s40, s40, 0x20000
	s_addc_u32 s41, s41, 0
	global_load_dword v25, v0, s[38:39] nt
	global_load_dword v26, v1, s[40:41] nt
	s_add_u32 s38, s38, 0x20000
	s_addc_u32 s39, s39, 0
	s_add_u32 s40, s40, 0x20000
	s_addc_u32 s41, s41, 0
	global_load_dword v27, v0, s[38:39] nt
	global_load_dword v28, v1, s[40:41] nt
	s_add_u32 s38, s38, 0x20000
	s_addc_u32 s39, s39, 0
	s_add_u32 s40, s40, 0x20000
	s_addc_u32 s41, s41, 0
	global_load_dword v29, v0, s[38:39] nt
	global_load_dword v30, v1, s[40:41] nt
	s_add_u32 s38, s38, 0x20000
	s_addc_u32 s39, s39, 0
	s_add_u32 s40, s40, 0x20000
	s_addc_u32 s41, s41, 0
	global_load_dword v31, v0, s[38:39] nt
	global_load_dword v32, v1, s[40:41] nt
	s_add_u32 s38, s38, 0x20000
	s_addc_u32 s39, s39, 0
	s_add_u32 s40, s40, 0x20000
	s_addc_u32 s41, s41, 0
	global_load_dword v33, v0, s[38:39] nt
	global_load_dword v34, v1, s[40:41] nt
	s_add_u32 s38, s38, 0x20000
	s_addc_u32 s39, s39, 0
	s_add_u32 s40, s40, 0x20000
	s_addc_u32 s41, s41, 0
	global_load_dword v35, v0, s[38:39] nt
	global_load_dword v36, v1, s[40:41] nt
	s_add_u32 s38, s38, 0x20000
	s_addc_u32 s39, s39, 0
	s_add_u32 s40, s40, 0x20000
	s_addc_u32 s41, s41, 0
	global_load_dword v37, v0, s[38:39] nt
	global_load_dword v38, v1, s[40:41] nt
	s_add_u32 s38, s38, 0x20000
	s_addc_u32 s39, s39, 0
	s_add_u32 s40, s40, 0x20000
	s_addc_u32 s41, s41, 0
	global_load_dword v40, v0, s[38:39] nt
	global_load_dword v41, v1, s[40:41] nt
	s_add_u32 s38, s38, 0x20000
	s_addc_u32 s39, s39, 0
	s_add_u32 s40, s40, 0x20000
	s_addc_u32 s41, s41, 0
	s_waitcnt vmcnt(30)
	v_cvt_pk_bf16_f32 v8, v8, v20
	v_cvt_pk_bf16_f32 v9, v9, v20
	global_store_short v3, v8, s[44:45]
	global_store_short v5, v9, s[46:47]
	s_add_u32 s44, s44, 0x14000
	s_addc_u32 s45, s45, 0
	s_add_u32 s46, s46, 0x14000
	s_addc_u32 s47, s47, 0
	global_load_dword v8, v0, s[38:39] nt
	global_load_dword v9, v1, s[40:41] nt
	s_add_u32 s38, s38, 0x20000
	s_addc_u32 s39, s39, 0
	s_add_u32 s40, s40, 0x20000
	s_addc_u32 s41, s41, 0
	s_waitcnt vmcnt(32)
	v_cvt_pk_bf16_f32 v10, v10, v20
	v_cvt_pk_bf16_f32 v11, v11, v20
	global_store_short v3, v10, s[44:45]
	global_store_short v5, v11, s[46:47]
	s_add_u32 s44, s44, 0x14000
	s_addc_u32 s45, s45, 0
	s_add_u32 s46, s46, 0x14000
	s_addc_u32 s47, s47, 0
	global_load_dword v10, v0, s[38:39] nt
	global_load_dword v11, v1, s[40:41] nt
	s_add_u32 s38, s38, 0x20000
	s_addc_u32 s39, s39, 0
	s_add_u32 s40, s40, 0x20000
	s_addc_u32 s41, s41, 0
	s_waitcnt vmcnt(34)
	v_cvt_pk_bf16_f32 v12, v12, v20
	v_cvt_pk_bf16_f32 v13, v13, v20
	global_store_short v3, v12, s[44:45]
	global_store_short v5, v13, s[46:47]
	s_add_u32 s44, s44, 0x14000
	s_addc_u32 s45, s45, 0
	s_add_u32 s46, s46, 0x14000
	s_addc_u32 s47, s47, 0
	global_load_dword v12, v0, s[38:39] nt
	global_load_dword v13, v1, s[40:41] nt
	s_add_u32 s38, s38, 0x20000
	s_addc_u32 s39, s39, 0
	s_add_u32 s40, s40, 0x20000
	s_addc_u32 s41, s41, 0
	s_waitcnt vmcnt(36)
	v_cvt_pk_bf16_f32 v14, v14, v20
	v_cvt_pk_bf16_f32 v15, v15, v20
	global_store_short v3, v14, s[44:45]
	global_store_short v5, v15, s[46:47]
	s_add_u32 s44, s44, 0x14000
	s_addc_u32 s45, s45, 0
	s_add_u32 s46, s46, 0x14000
	s_addc_u32 s47, s47, 0
	global_load_dword v14, v0, s[38:39] nt
	global_load_dword v15, v1, s[40:41] nt
	s_add_u32 s38, s38, 0x20000
	s_addc_u32 s39, s39, 0
	s_add_u32 s40, s40, 0x20000
	s_addc_u32 s41, s41, 0
	s_waitcnt vmcnt(38)
	v_cvt_pk_bf16_f32 v16, v16, v20
	v_cvt_pk_bf16_f32 v17, v17, v20
	global_store_short v3, v16, s[44:45]
	global_store_short v5, v17, s[46:47]
	s_add_u32 s44, s44, 0x14000
	s_addc_u32 s45, s45, 0
	s_add_u32 s46, s46, 0x14000
	s_addc_u32 s47, s47, 0
	global_load_dword v16, v0, s[38:39] nt
	global_load_dword v17, v1, s[40:41] nt
	s_add_u32 s38, s38, 0x20000
	s_addc_u32 s39, s39, 0
	s_add_u32 s40, s40, 0x20000
	s_addc_u32 s41, s41, 0
	s_waitcnt vmcnt(40)
	v_cvt_pk_bf16_f32 v18, v18, v20
	v_cvt_pk_bf16_f32 v19, v19, v20
	global_store_short v3, v18, s[44:45]
	global_store_short v5, v19, s[46:47]
	s_add_u32 s44, s44, 0x14000
	s_addc_u32 s45, s45, 0
	s_add_u32 s46, s46, 0x14000
	s_addc_u32 s47, s47, 0
	global_load_dword v18, v0, s[38:39] nt
	global_load_dword v19, v1, s[40:41] nt
	s_add_u32 s38, s38, 0x20000
	s_addc_u32 s39, s39, 0
	s_add_u32 s40, s40, 0x20000
	s_addc_u32 s41, s41, 0
	s_waitcnt vmcnt(42)
	v_cvt_pk_bf16_f32 v21, v21, v20
	v_cvt_pk_bf16_f32 v22, v22, v20
	global_store_short v3, v21, s[44:45]
	global_store_short v5, v22, s[46:47]
	s_add_u32 s44, s44, 0x14000
	s_addc_u32 s45, s45, 0
	s_add_u32 s46, s46, 0x14000
	s_addc_u32 s47, s47, 0
	global_load_dword v21, v0, s[38:39] nt
	global_load_dword v22, v1, s[40:41] nt
	s_add_u32 s38, s38, 0x20000
	s_addc_u32 s39, s39, 0
	s_add_u32 s40, s40, 0x20000
	s_addc_u32 s41, s41, 0
	s_waitcnt vmcnt(44)
	v_cvt_pk_bf16_f32 v23, v23, v20
	v_cvt_pk_bf16_f32 v24, v24, v20
	global_store_short v3, v23, s[44:45]
	global_store_short v5, v24, s[46:47]
	s_add_u32 s44, s44, 0x14000
	s_addc_u32 s45, s45, 0
	s_add_u32 s46, s46, 0x14000
	s_addc_u32 s47, s47, 0
	global_load_dword v23, v0, s[38:39] nt
	global_load_dword v24, v1, s[40:41] nt
	s_add_u32 s38, s38, 0x20000
	s_addc_u32 s39, s39, 0
	s_add_u32 s40, s40, 0x20000
	s_addc_u32 s41, s41, 0
	s_waitcnt vmcnt(46)
	v_cvt_pk_bf16_f32 v25, v25, v20
	v_cvt_pk_bf16_f32 v26, v26, v20
	global_store_short v3, v25, s[44:45]
	global_store_short v5, v26, s[46:47]
	s_add_u32 s44, s44, 0x14000
	s_addc_u32 s45, s45, 0
	s_add_u32 s46, s46, 0x14000
	s_addc_u32 s47, s47, 0
	global_load_dword v25, v0, s[38:39] nt
	global_load_dword v26, v1, s[40:41] nt
	s_add_u32 s38, s38, 0x20000
	s_addc_u32 s39, s39, 0
	s_add_u32 s40, s40, 0x20000
	s_addc_u32 s41, s41, 0
	s_waitcnt vmcnt(48)
	v_cvt_pk_bf16_f32 v27, v27, v20
	v_cvt_pk_bf16_f32 v28, v28, v20
	global_store_short v3, v27, s[44:45]
	global_store_short v5, v28, s[46:47]
	s_add_u32 s44, s44, 0x14000
	s_addc_u32 s45, s45, 0
	s_add_u32 s46, s46, 0x14000
	s_addc_u32 s47, s47, 0
	global_load_dword v27, v0, s[38:39] nt
	global_load_dword v28, v1, s[40:41] nt
	s_add_u32 s38, s38, 0x20000
	s_addc_u32 s39, s39, 0
	s_add_u32 s40, s40, 0x20000
	s_addc_u32 s41, s41, 0
	s_waitcnt vmcnt(50)
	v_cvt_pk_bf16_f32 v29, v29, v20
	v_cvt_pk_bf16_f32 v30, v30, v20
	global_store_short v3, v29, s[44:45]
	global_store_short v5, v30, s[46:47]
	s_add_u32 s44, s44, 0x14000
	s_addc_u32 s45, s45, 0
	s_add_u32 s46, s46, 0x14000
	s_addc_u32 s47, s47, 0
	global_load_dword v29, v0, s[38:39] nt
	global_load_dword v30, v1, s[40:41] nt
	s_add_u32 s38, s38, 0x20000
	s_addc_u32 s39, s39, 0
	s_add_u32 s40, s40, 0x20000
	s_addc_u32 s41, s41, 0
	s_waitcnt vmcnt(52)
	v_cvt_pk_bf16_f32 v31, v31, v20
	v_cvt_pk_bf16_f32 v32, v32, v20
	global_store_short v3, v31, s[44:45]
	global_store_short v5, v32, s[46:47]
	s_add_u32 s44, s44, 0x14000
	s_addc_u32 s45, s45, 0
	s_add_u32 s46, s46, 0x14000
	s_addc_u32 s47, s47, 0
	global_load_dword v31, v0, s[38:39] nt
	global_load_dword v32, v1, s[40:41] nt
	s_add_u32 s38, s38, 0x20000
	s_addc_u32 s39, s39, 0
	s_add_u32 s40, s40, 0x20000
	s_addc_u32 s41, s41, 0
	s_waitcnt vmcnt(54)
	v_cvt_pk_bf16_f32 v33, v33, v20
	v_cvt_pk_bf16_f32 v34, v34, v20
	global_store_short v3, v33, s[44:45]
	global_store_short v5, v34, s[46:47]
	s_add_u32 s44, s44, 0x14000
	s_addc_u32 s45, s45, 0
	s_add_u32 s46, s46, 0x14000
	s_addc_u32 s47, s47, 0
	global_load_dword v33, v0, s[38:39] nt
	global_load_dword v34, v1, s[40:41] nt
	s_add_u32 s38, s38, 0x20000
	s_addc_u32 s39, s39, 0
	s_add_u32 s40, s40, 0x20000
	s_addc_u32 s41, s41, 0
	s_waitcnt vmcnt(56)
	v_cvt_pk_bf16_f32 v35, v35, v20
	v_cvt_pk_bf16_f32 v36, v36, v20
	global_store_short v3, v35, s[44:45]
	global_store_short v5, v36, s[46:47]
	s_add_u32 s44, s44, 0x14000
	s_addc_u32 s45, s45, 0
	s_add_u32 s46, s46, 0x14000
	s_addc_u32 s47, s47, 0
	global_load_dword v35, v0, s[38:39] nt
	global_load_dword v36, v1, s[40:41] nt
	s_add_u32 s38, s38, 0x20000
	s_addc_u32 s39, s39, 0
	s_add_u32 s40, s40, 0x20000
	s_addc_u32 s41, s41, 0
	s_waitcnt vmcnt(58)
	v_cvt_pk_bf16_f32 v37, v37, v20
	v_cvt_pk_bf16_f32 v38, v38, v20
	global_store_short v3, v37, s[44:45]
	global_store_short v5, v38, s[46:47]
	s_add_u32 s44, s44, 0x14000
	s_addc_u32 s45, s45, 0
	s_add_u32 s46, s46, 0x14000
	s_addc_u32 s47, s47, 0
	global_load_dword v37, v0, s[38:39] nt
	global_load_dword v38, v1, s[40:41] nt
	s_add_u32 s38, s38, 0x20000
	s_addc_u32 s39, s39, 0
	s_add_u32 s40, s40, 0x20000
	s_addc_u32 s41, s41, 0
	s_waitcnt vmcnt(60)
	v_cvt_pk_bf16_f32 v40, v40, v20
	v_cvt_pk_bf16_f32 v41, v41, v20
	global_store_short v3, v40, s[44:45]
	global_store_short v5, v41, s[46:47]
	s_add_u32 s44, s44, 0x14000
	s_addc_u32 s45, s45, 0
	s_add_u32 s46, s46, 0x14000
	s_addc_u32 s47, s47, 0
	global_load_dword v40, v0, s[38:39] nt
	global_load_dword v41, v1, s[40:41] nt
	s_waitcnt vmcnt(60)
	v_cvt_pk_bf16_f32 v8, v8, v20
	v_cvt_pk_bf16_f32 v9, v9, v20
	global_store_short v3, v8, s[44:45]
	global_store_short v5, v9, s[46:47]
	s_add_u32 s44, s44, 0x14000
	s_addc_u32 s45, s45, 0
	s_add_u32 s46, s46, 0x14000
	s_addc_u32 s47, s47, 0
	s_waitcnt vmcnt(58)
	v_cvt_pk_bf16_f32 v10, v10, v20
	v_cvt_pk_bf16_f32 v11, v11, v20
	global_store_short v3, v10, s[44:45]
	global_store_short v5, v11, s[46:47]
	s_add_u32 s44, s44, 0x14000
	s_addc_u32 s45, s45, 0
	s_add_u32 s46, s46, 0x14000
	s_addc_u32 s47, s47, 0
	s_waitcnt vmcnt(56)
	v_cvt_pk_bf16_f32 v12, v12, v20
	v_cvt_pk_bf16_f32 v13, v13, v20
	global_store_short v3, v12, s[44:45]
	global_store_short v5, v13, s[46:47]
	s_add_u32 s44, s44, 0x14000
	s_addc_u32 s45, s45, 0
	s_add_u32 s46, s46, 0x14000
	s_addc_u32 s47, s47, 0
	s_waitcnt vmcnt(54)
	v_cvt_pk_bf16_f32 v14, v14, v20
	v_cvt_pk_bf16_f32 v15, v15, v20
	global_store_short v3, v14, s[44:45]
	global_store_short v5, v15, s[46:47]
	s_add_u32 s44, s44, 0x14000
	s_addc_u32 s45, s45, 0
	s_add_u32 s46, s46, 0x14000
	s_addc_u32 s47, s47, 0
	s_waitcnt vmcnt(52)
	v_cvt_pk_bf16_f32 v16, v16, v20
	v_cvt_pk_bf16_f32 v17, v17, v20
	global_store_short v3, v16, s[44:45]
	global_store_short v5, v17, s[46:47]
	s_add_u32 s44, s44, 0x14000
	s_addc_u32 s45, s45, 0
	s_add_u32 s46, s46, 0x14000
	s_addc_u32 s47, s47, 0
	s_waitcnt vmcnt(50)
	v_cvt_pk_bf16_f32 v18, v18, v20
	v_cvt_pk_bf16_f32 v19, v19, v20
	global_store_short v3, v18, s[44:45]
	global_store_short v5, v19, s[46:47]
	s_add_u32 s44, s44, 0x14000
	s_addc_u32 s45, s45, 0
	s_add_u32 s46, s46, 0x14000
	s_addc_u32 s47, s47, 0
	s_waitcnt vmcnt(48)
	v_cvt_pk_bf16_f32 v21, v21, v20
	v_cvt_pk_bf16_f32 v22, v22, v20
	global_store_short v3, v21, s[44:45]
	global_store_short v5, v22, s[46:47]
	s_add_u32 s44, s44, 0x14000
	s_addc_u32 s45, s45, 0
	s_add_u32 s46, s46, 0x14000
	s_addc_u32 s47, s47, 0
	s_waitcnt vmcnt(46)
	v_cvt_pk_bf16_f32 v23, v23, v20
	v_cvt_pk_bf16_f32 v24, v24, v20
	global_store_short v3, v23, s[44:45]
	global_store_short v5, v24, s[46:47]
	s_add_u32 s44, s44, 0x14000
	s_addc_u32 s45, s45, 0
	s_add_u32 s46, s46, 0x14000
	s_addc_u32 s47, s47, 0
	s_waitcnt vmcnt(44)
	v_cvt_pk_bf16_f32 v25, v25, v20
	v_cvt_pk_bf16_f32 v26, v26, v20
	global_store_short v3, v25, s[44:45]
	global_store_short v5, v26, s[46:47]
	s_add_u32 s44, s44, 0x14000
	s_addc_u32 s45, s45, 0
	s_add_u32 s46, s46, 0x14000
	s_addc_u32 s47, s47, 0
	s_waitcnt vmcnt(42)
	v_cvt_pk_bf16_f32 v27, v27, v20
	v_cvt_pk_bf16_f32 v28, v28, v20
	global_store_short v3, v27, s[44:45]
	global_store_short v5, v28, s[46:47]
	s_add_u32 s44, s44, 0x14000
	s_addc_u32 s45, s45, 0
	s_add_u32 s46, s46, 0x14000
	s_addc_u32 s47, s47, 0
	s_waitcnt vmcnt(40)
	v_cvt_pk_bf16_f32 v29, v29, v20
	v_cvt_pk_bf16_f32 v30, v30, v20
	global_store_short v3, v29, s[44:45]
	global_store_short v5, v30, s[46:47]
	s_add_u32 s44, s44, 0x14000
	s_addc_u32 s45, s45, 0
	s_add_u32 s46, s46, 0x14000
	s_addc_u32 s47, s47, 0
	s_waitcnt vmcnt(38)
	v_cvt_pk_bf16_f32 v31, v31, v20
	v_cvt_pk_bf16_f32 v32, v32, v20
	global_store_short v3, v31, s[44:45]
	global_store_short v5, v32, s[46:47]
	s_add_u32 s44, s44, 0x14000
	s_addc_u32 s45, s45, 0
	s_add_u32 s46, s46, 0x14000
	s_addc_u32 s47, s47, 0
	s_waitcnt vmcnt(36)
	v_cvt_pk_bf16_f32 v33, v33, v20
	v_cvt_pk_bf16_f32 v34, v34, v20
	global_store_short v3, v33, s[44:45]
	global_store_short v5, v34, s[46:47]
	s_add_u32 s44, s44, 0x14000
	s_addc_u32 s45, s45, 0
	s_add_u32 s46, s46, 0x14000
	s_addc_u32 s47, s47, 0
	s_waitcnt vmcnt(34)
	v_cvt_pk_bf16_f32 v35, v35, v20
	v_cvt_pk_bf16_f32 v36, v36, v20
	global_store_short v3, v35, s[44:45]
	global_store_short v5, v36, s[46:47]
	s_add_u32 s44, s44, 0x14000
	s_addc_u32 s45, s45, 0
	s_add_u32 s46, s46, 0x14000
	s_addc_u32 s47, s47, 0
	s_waitcnt vmcnt(32)
	v_cvt_pk_bf16_f32 v37, v37, v20
	v_cvt_pk_bf16_f32 v38, v38, v20
	global_store_short v3, v37, s[44:45]
	global_store_short v5, v38, s[46:47]
	s_add_u32 s44, s44, 0x14000
	s_addc_u32 s45, s45, 0
	s_add_u32 s46, s46, 0x14000
	s_addc_u32 s47, s47, 0
	s_waitcnt vmcnt(30)
	v_cvt_pk_bf16_f32 v40, v40, v20
	v_cvt_pk_bf16_f32 v41, v41, v20
	global_store_short v3, v40, s[44:45]
	global_store_short v5, v41, s[46:47]
	s_branch .LBB0_271
